# mixer epilogue: 8 row-sum atomics per wave merged into 2 full-wave atomics (lane quarter picks the row group); on top of v44
# baseline (speedup 1.0000x reference)
.Lxr2_3:
.LBB0_1073:
	v_mul_f32_e32 v88, v192, v192
	v_mul_f32_e32 v89, v190, v190
	v_fmac_f32_e32 v88, v193, v193
	v_fmac_f32_e32 v89, v191, v191
	v_add_f32_e32 v88, v89, v88
	v_mul_f32_e32 v89, v174, v174
	v_mul_f32_e32 v96, v177, v177
	v_fmac_f32_e32 v89, v175, v175
	v_fmac_f32_e32 v96, v176, v176
	v_add_f32_e32 v89, v96, v89
	v_add_f32_e32 v88, v89, v88
	v_mul_f32_e32 v89, v198, v198
	v_mul_f32_e32 v96, v194, v194
	v_fmac_f32_e32 v89, v199, v199
	v_fmac_f32_e32 v96, v195, v195
	v_add_f32_e32 v89, v96, v89
	v_mul_f32_e32 v96, v110, v110
	v_mul_f32_e32 v97, v113, v113
	v_fmac_f32_e32 v96, v111, v111
	v_fmac_f32_e32 v97, v112, v112
	v_add_f32_e32 v96, v97, v96
	v_add_f32_e32 v89, v96, v89
	v_add_f32_e32 v96, v88, v89
	v_lshl_add_u64 v[88:89], v[226:227], 0, v[120:121]
	s_waitcnt vmcnt(0)
	v_pk_fma_f32 v[26:27], v[26:27], v[74:75], v[62:63]
	v_lshlrev_b64 v[62:63], 1, v[88:89]
	v_pk_fma_f32 v[32:33], v[32:33], v[80:81], v[60:61]
	v_pk_fma_f32 v[30:31], v[30:31], v[78:79], v[58:59]
	v_pk_fma_f32 v[28:29], v[28:29], v[76:77], v[64:65]
	v_cvt_pk_bf16_f32 v58, v30, v31
	v_cvt_pk_bf16_f32 v59, v32, v33
	v_lshl_add_u64 v[64:65], s[12:13], 0, v[62:63]
	v_cvt_pk_bf16_f32 v60, v26, v27
	v_cvt_pk_bf16_f32 v61, v28, v29
	v_lshl_add_u64 v[62:63], s[18:19], 0, v[62:63]
	v_pk_mul_f32 v[64:65], v[68:69], v[28:29]
	v_pk_mul_f32 v[58:59], v[70:71], v[30:31]
	v_pk_mul_f32 v[60:61], v[72:73], v[32:33]
	v_cvt_pk_bf16_f32 v58, v58, v59
	v_pk_mul_f32 v[88:89], v[66:67], v[26:27]
	v_cvt_pk_bf16_f32 v59, v60, v61
	v_pk_fma_f32 v[18:19], v[18:19], v[74:75], v[54:55]
	v_cvt_pk_bf16_f32 v60, v88, v89
	v_cvt_pk_bf16_f32 v61, v64, v65
	flat_store_dwordx4 v[62:63], v[58:61]
	v_pk_fma_f32 v[24:25], v[24:25], v[80:81], v[52:53]
	v_pk_fma_f32 v[22:23], v[22:23], v[78:79], v[50:51]
	v_lshl_add_u64 v[58:59], v[228:229], 0, v[120:121]
	v_lshlrev_b64 v[54:55], 1, v[58:59]
	v_pk_fma_f32 v[20:21], v[20:21], v[76:77], v[56:57]
	v_cvt_pk_bf16_f32 v50, v22, v23
	v_cvt_pk_bf16_f32 v51, v24, v25
	v_lshl_add_u64 v[56:57], s[12:13], 0, v[54:55]
	v_cvt_pk_bf16_f32 v52, v18, v19
	v_cvt_pk_bf16_f32 v53, v20, v21
	v_lshl_add_u64 v[54:55], s[18:19], 0, v[54:55]
	v_pk_mul_f32 v[56:57], v[68:69], v[20:21]
	v_pk_mul_f32 v[50:51], v[70:71], v[22:23]
	v_pk_mul_f32 v[52:53], v[72:73], v[24:25]
	v_cvt_pk_bf16_f32 v50, v50, v51
	v_pk_mul_f32 v[58:59], v[66:67], v[18:19]
	v_cvt_pk_bf16_f32 v51, v52, v53
	v_pk_fma_f32 v[10:11], v[10:11], v[74:75], v[46:47]
	v_cvt_pk_bf16_f32 v52, v58, v59
	v_cvt_pk_bf16_f32 v53, v56, v57
	flat_store_dwordx4 v[54:55], v[50:53]
	v_pk_fma_f32 v[16:17], v[16:17], v[80:81], v[44:45]
	v_pk_fma_f32 v[14:15], v[14:15], v[78:79], v[42:43]
	v_lshl_add_u64 v[50:51], v[230:231], 0, v[120:121]
	v_lshlrev_b64 v[46:47], 1, v[50:51]
	v_pk_fma_f32 v[12:13], v[12:13], v[76:77], v[48:49]
	v_cvt_pk_bf16_f32 v42, v14, v15
	v_cvt_pk_bf16_f32 v43, v16, v17
	v_lshl_add_u64 v[48:49], s[12:13], 0, v[46:47]
	v_cvt_pk_bf16_f32 v44, v10, v11
	v_cvt_pk_bf16_f32 v45, v12, v13
	v_lshl_add_u64 v[46:47], s[18:19], 0, v[46:47]
	v_pk_mul_f32 v[48:49], v[68:69], v[12:13]
	v_pk_mul_f32 v[42:43], v[70:71], v[14:15]
	v_pk_mul_f32 v[44:45], v[72:73], v[16:17]
	v_cvt_pk_bf16_f32 v42, v42, v43
	v_pk_mul_f32 v[50:51], v[66:67], v[10:11]
	v_cvt_pk_bf16_f32 v43, v44, v45
	v_pk_fma_f32 v[2:3], v[2:3], v[74:75], v[38:39]
	v_cvt_pk_bf16_f32 v44, v50, v51
	v_cvt_pk_bf16_f32 v45, v48, v49
	flat_store_dwordx4 v[46:47], v[42:45]
	v_pk_fma_f32 v[8:9], v[8:9], v[80:81], v[36:37]
	v_pk_fma_f32 v[6:7], v[6:7], v[78:79], v[34:35]
	v_lshl_add_u64 v[42:43], v[128:129], 0, v[120:121]
	v_lshlrev_b64 v[38:39], 1, v[42:43]
	v_pk_fma_f32 v[4:5], v[4:5], v[76:77], v[40:41]
	v_cvt_pk_bf16_f32 v34, v6, v7
	v_cvt_pk_bf16_f32 v35, v8, v9
	v_cvt_pk_bf16_f32 v36, v2, v3
	v_lshl_add_u64 v[40:41], s[12:13], 0, v[38:39]
	v_cvt_pk_bf16_f32 v37, v4, v5
	v_pk_mul_f32 v[42:43], v[66:67], v[2:3]
	v_lshl_add_u64 v[38:39], s[18:19], 0, v[38:39]
	v_pk_mul_f32 v[36:37], v[72:73], v[8:9]
	v_pk_mul_f32 v[34:35], v[70:71], v[6:7]
	v_pk_mul_f32 v[40:41], v[68:69], v[4:5]
	v_cvt_pk_bf16_f32 v34, v34, v35
	v_cvt_pk_bf16_f32 v35, v36, v37
	v_cvt_pk_bf16_f32 v36, v42, v43
	ds_swizzle_b32 v42, v96 offset:swizzle(SWAP,16)
	v_cvt_pk_bf16_f32 v37, v40, v41
	flat_store_dwordx4 v[38:39], v[34:37]
	v_cmp_eq_u32_e32 vcc, 0, v245
	s_waitcnt lgkmcnt(0)
	v_add_f32_e32 v36, v96, v42
	v_mov_b32_e32 v37, v36
	s_nop 1
	v_permlane32_swap_b32_e32 v36, v37
	v_lshl_add_u64 v[34:35], v[178:179], 3, s[20:21]
	v_cmp_eq_u32_e64 s[88:89], 1, v245
	v_cmp_eq_u32_e64 s[90:91], 2, v245
	v_cmp_eq_u32_e64 s[96:97], 3, v245
	v_lshlrev_b32_e32 v54, 7, v245
	v_mov_b32_e32 v55, 0
	v_lshl_add_u64 v[54:55], v[34:35], 0, v[54:55]
	s_nop 1
	v_add_f32_e32 v46, v36, v37
.LBB0_1075:
	v_mul_f32_e32 v36, v172, v172
	v_mul_f32_e32 v37, v170, v170
	v_fmac_f32_e32 v36, v173, v173
	v_fmac_f32_e32 v37, v171, v171
	v_add_f32_e32 v36, v37, v36
	v_mul_f32_e32 v37, v166, v166
	v_mul_f32_e32 v38, v169, v169
	v_fmac_f32_e32 v37, v167, v167
	v_fmac_f32_e32 v38, v168, v168
	v_add_f32_e32 v37, v38, v37
	v_add_f32_e32 v36, v37, v36
	v_mul_f32_e32 v37, v108, v108
	v_mul_f32_e32 v38, v106, v106
	v_fmac_f32_e32 v37, v109, v109
	v_fmac_f32_e32 v38, v107, v107
	v_add_f32_e32 v37, v38, v37
	v_mul_f32_e32 v38, v102, v102
	v_mul_f32_e32 v39, v105, v105
	v_fmac_f32_e32 v38, v103, v103
	v_fmac_f32_e32 v39, v104, v104
	v_add_f32_e32 v38, v39, v38
	v_add_f32_e32 v37, v38, v37
	v_add_f32_e32 v36, v36, v37
	ds_swizzle_b32 v37, v36 offset:swizzle(SWAP,16)
	s_waitcnt lgkmcnt(0)
	v_add_f32_e32 v36, v36, v37
	v_mov_b32_e32 v37, v36
	s_nop 1
	v_permlane32_swap_b32_e32 v36, v37
	s_nop 1
	v_add_f32_e32 v47, v36, v37
.LBB0_1077:
	v_mul_f32_e32 v36, v164, v164
	v_mul_f32_e32 v37, v162, v162
	v_fmac_f32_e32 v36, v165, v165
	v_fmac_f32_e32 v37, v163, v163
	v_add_f32_e32 v36, v37, v36
	v_mul_f32_e32 v37, v158, v158
	v_mul_f32_e32 v38, v157, v157
	v_fmac_f32_e32 v37, v159, v159
	v_fmac_f32_e32 v38, v156, v156
	v_add_f32_e32 v37, v38, v37
	v_add_f32_e32 v36, v37, v36
	v_mul_f32_e32 v37, v100, v100
	v_mul_f32_e32 v38, v98, v98
	v_fmac_f32_e32 v37, v101, v101
	v_fmac_f32_e32 v38, v99, v99
	v_add_f32_e32 v37, v38, v37
	v_mul_f32_e32 v38, v94, v94
	v_mul_f32_e32 v39, v93, v93
	v_fmac_f32_e32 v38, v95, v95
	v_fmac_f32_e32 v39, v92, v92
	v_add_f32_e32 v38, v39, v38
	v_add_f32_e32 v37, v38, v37
	v_add_f32_e32 v36, v36, v37
	ds_swizzle_b32 v37, v36 offset:swizzle(SWAP,16)
	s_waitcnt lgkmcnt(0)
	v_add_f32_e32 v36, v36, v37
	v_mov_b32_e32 v37, v36
	s_nop 1
	v_permlane32_swap_b32_e32 v36, v37
	s_nop 1
	v_add_f32_e32 v48, v36, v37
.LBB0_1079:
	v_mul_f32_e32 v36, v154, v154
	v_mul_f32_e32 v37, v148, v148
	v_fmac_f32_e32 v36, v155, v155
	v_fmac_f32_e32 v37, v149, v149
	v_add_f32_e32 v36, v37, v36
	v_mul_f32_e32 v37, v150, v150
	v_mul_f32_e32 v38, v147, v147
	v_fmac_f32_e32 v37, v151, v151
	v_fmac_f32_e32 v38, v146, v146
	v_add_f32_e32 v37, v38, v37
	v_add_f32_e32 v36, v37, v36
	v_mul_f32_e32 v37, v90, v90
	v_mul_f32_e32 v38, v84, v84
	v_fmac_f32_e32 v37, v91, v91
	v_fmac_f32_e32 v38, v85, v85
	v_add_f32_e32 v37, v38, v37
	v_mul_f32_e32 v38, v86, v86
	v_mul_f32_e32 v39, v83, v83
	v_fmac_f32_e32 v38, v87, v87
	v_fmac_f32_e32 v39, v82, v82
	v_add_f32_e32 v38, v39, v38
	v_add_f32_e32 v37, v38, v37
	v_add_f32_e32 v36, v36, v37
	ds_swizzle_b32 v37, v36 offset:swizzle(SWAP,16)
	s_waitcnt lgkmcnt(0)
	v_add_f32_e32 v36, v36, v37
	v_mov_b32_e32 v37, v36
	s_nop 1
	v_permlane32_swap_b32_e32 v36, v37
	s_nop 1
	v_add_f32_e32 v36, v36, v37
	v_cndmask_b32_e64 v50, v46, v47, s[88:89]
	v_cndmask_b32_e64 v50, v50, v48, s[90:91]
	v_cndmask_b32_e64 v50, v50, v36, s[96:97]
	v_mul_f32_e32 v50, 0x49800000, v50
	v_trunc_f32_e32 v50, v50
	v_mul_f32_e64 v51, |v50|, s78
	v_floor_f32_e32 v51, v51
	v_fma_f32 v52, v51, s74, |v50|
	v_cvt_u32_f32_e32 v52, v52
	v_cvt_u32_f32_e32 v51, v51
	v_ashrrev_i32_e32 v53, 31, v50
	v_xor_b32_e32 v50, v52, v53
	v_xor_b32_e32 v51, v51, v53
	v_sub_co_u32_e64 v50, s[8:9], v50, v53
	s_nop 1
	v_subb_co_u32_e64 v51, s[8:9], v51, v53, s[8:9]
	global_atomic_add_x2 v[54:55], v[50:51], off
.LBB0_1081:
	v_mul_f32_e32 v36, v152, v152
	v_mul_f32_e32 v37, v140, v140
	v_fmac_f32_e32 v36, v153, v153
	v_fmac_f32_e32 v37, v141, v141
	v_mul_f32_e32 v30, v30, v30
	v_mul_f32_e32 v26, v26, v26
	v_add_f32_e32 v36, v37, v36
	v_mul_f32_e32 v37, v144, v144
	v_mul_f32_e32 v38, v139, v139
	v_fmac_f32_e32 v30, v31, v31
	v_mul_f32_e32 v31, v32, v32
	v_fmac_f32_e32 v26, v27, v27
	v_mul_f32_e32 v27, v29, v29
	v_fmac_f32_e32 v37, v145, v145
	v_fmac_f32_e32 v38, v138, v138
	v_fmac_f32_e32 v31, v33, v33
	v_fmac_f32_e32 v27, v28, v28
	v_add_f32_e32 v37, v38, v37
	v_add_f32_e32 v30, v31, v30
	v_add_f32_e32 v26, v27, v26
	v_add_f32_e32 v36, v37, v36
	v_add_f32_e32 v26, v26, v30
	v_add_f32_e32 v26, v36, v26
	ds_swizzle_b32 v27, v26 offset:swizzle(SWAP,16)
	s_waitcnt lgkmcnt(0)
	v_add_f32_e32 v26, v26, v27
	v_mov_b32_e32 v27, v26
	s_nop 1
	v_permlane32_swap_b32_e32 v26, v27
	s_nop 1
	v_add_f32_e32 v46, v26, v27
.LBB0_1083:
	v_mul_f32_e32 v26, v160, v160
	v_mul_f32_e32 v27, v142, v142
	v_fmac_f32_e32 v26, v161, v161
	v_fmac_f32_e32 v27, v143, v143
	v_mul_f32_e32 v22, v22, v22
	v_mul_f32_e32 v18, v18, v18
	v_add_f32_e32 v26, v27, v26
	v_mul_f32_e32 v27, v134, v134
	v_mul_f32_e32 v28, v137, v137
	v_fmac_f32_e32 v22, v23, v23
	v_mul_f32_e32 v23, v24, v24
	v_fmac_f32_e32 v18, v19, v19
	v_mul_f32_e32 v19, v21, v21
	v_fmac_f32_e32 v27, v135, v135
	v_fmac_f32_e32 v28, v136, v136
	v_fmac_f32_e32 v23, v25, v25
	v_fmac_f32_e32 v19, v20, v20
	v_add_f32_e32 v27, v28, v27
	v_add_f32_e32 v22, v23, v22
	v_add_f32_e32 v18, v19, v18
	v_add_f32_e32 v26, v27, v26
	v_add_f32_e32 v18, v18, v22
	v_add_f32_e32 v18, v26, v18
	ds_swizzle_b32 v19, v18 offset:swizzle(SWAP,16)
	s_waitcnt lgkmcnt(0)
	v_add_f32_e32 v18, v18, v19
	v_mov_b32_e32 v19, v18
	s_nop 1
	v_permlane32_swap_b32_e32 v18, v19
	s_nop 1
	v_add_f32_e32 v47, v18, v19
.LBB0_1085:
	v_mul_f32_e32 v18, v132, v132
	v_mul_f32_e32 v19, v130, v130
	v_fmac_f32_e32 v18, v133, v133
	v_fmac_f32_e32 v19, v131, v131
	v_mul_f32_e32 v14, v14, v14
	v_mul_f32_e32 v10, v10, v10
	v_add_f32_e32 v18, v19, v18
	v_mul_f32_e32 v19, v126, v126
	v_mul_f32_e32 v20, v125, v125
	v_fmac_f32_e32 v14, v15, v15
	v_mul_f32_e32 v15, v16, v16
	v_fmac_f32_e32 v10, v11, v11
	v_mul_f32_e32 v11, v13, v13
	v_fmac_f32_e32 v19, v127, v127
	v_fmac_f32_e32 v20, v124, v124
	v_fmac_f32_e32 v15, v17, v17
	v_fmac_f32_e32 v11, v12, v12
	v_add_f32_e32 v19, v20, v19
	v_add_f32_e32 v14, v15, v14
	v_add_f32_e32 v10, v11, v10
	v_add_f32_e32 v18, v19, v18
	v_add_f32_e32 v10, v10, v14
	v_add_f32_e32 v10, v18, v10
	ds_swizzle_b32 v11, v10 offset:swizzle(SWAP,16)
	s_waitcnt lgkmcnt(0)
	v_add_f32_e32 v10, v10, v11
	v_mov_b32_e32 v11, v10
	s_nop 1
	v_permlane32_swap_b32_e32 v10, v11
	s_nop 1
	v_add_f32_e32 v48, v10, v11
.LBB0_1087:
	v_mul_f32_e32 v10, v122, v122
	v_mul_f32_e32 v11, v116, v116
	v_fmac_f32_e32 v10, v123, v123
	v_fmac_f32_e32 v11, v117, v117
	v_mul_f32_e32 v6, v6, v6
	v_mul_f32_e32 v2, v2, v2
	v_add_f32_e32 v10, v11, v10
	v_mul_f32_e32 v11, v118, v118
	v_mul_f32_e32 v12, v115, v115
	v_fmac_f32_e32 v6, v7, v7
	v_mul_f32_e32 v7, v8, v8
	v_fmac_f32_e32 v2, v3, v3
	v_mul_f32_e32 v3, v5, v5
	v_fmac_f32_e32 v11, v119, v119
	v_fmac_f32_e32 v12, v114, v114
	v_fmac_f32_e32 v7, v9, v9
	v_fmac_f32_e32 v3, v4, v4
	v_add_f32_e32 v11, v12, v11
	v_add_f32_e32 v6, v7, v6
	v_add_f32_e32 v2, v3, v2
	v_add_f32_e32 v10, v11, v10
	v_add_f32_e32 v2, v2, v6
	v_add_f32_e32 v2, v10, v2
	ds_swizzle_b32 v3, v2 offset:swizzle(SWAP,16)
	s_waitcnt lgkmcnt(0)
	v_add_f32_e32 v2, v2, v3
	v_mov_b32_e32 v3, v2
	s_nop 1
	v_permlane32_swap_b32_e32 v2, v3
	s_nop 1
	v_add_f32_e32 v2, v2, v3
	v_cndmask_b32_e64 v50, v46, v47, s[88:89]
	v_cndmask_b32_e64 v50, v50, v48, s[90:91]
	v_cndmask_b32_e64 v50, v50, v2, s[96:97]
	v_mul_f32_e32 v50, 0x49800000, v50
	v_trunc_f32_e32 v50, v50
	v_mul_f32_e64 v51, |v50|, s78
	v_floor_f32_e32 v51, v51
	v_fma_f32 v52, v51, s74, |v50|
	v_cvt_u32_f32_e32 v52, v52
	v_cvt_u32_f32_e32 v51, v51
	v_ashrrev_i32_e32 v53, 31, v50
	v_xor_b32_e32 v50, v52, v53
	v_xor_b32_e32 v51, v51, v53
	v_sub_co_u32_e64 v50, s[8:9], v50, v53
	s_nop 1
	v_subb_co_u32_e64 v51, s[8:9], v51, v53, s[8:9]
	global_atomic_add_x2 v[54:55], v[50:51], off offset:1024
.LBB0_1089:
	s_and_b64 vcc, exec, s[6:7]
	s_mov_b64 s[6:7], -1
	s_cbranch_vccnz .LBB0_1034
	s_and_b64 vcc, exec, s[2:3]
	s_cbranch_vccnz .LBB0_1033
	s_barrier
	s_branch .LBB0_1033
